# full stack + final-norm hoist + nt gate stores + hand-scheduled unorm8 gate epilogue
# speedup vs baseline: 1.0162x; 1.0162x over previous
; __device__ __forceinline__ float sigmoid_f(float x) { return __builtin_amdgcn_rcpf(1.0f + __builtin_amdgcn_exp2f(-1.4426950409f * x)); }
;     __device__ __forceinline__ void body_gate(f32x4 (&acc)[2][2][4][2], const Unit& u, int wr, int wc, int fr, int fq, int gbase, const float (&rsv)[2][4]) const {
;         EPI_ROWS_BEGIN
;             const float rs = rsv[ai][m];
; #pragma unroll
;             for (int bj = 0; bj < 2; ++bj) { if (u.half != 0 && bj == 1) continue;
;                 const int gcol = gbase + (bj + (u.half == 2 ? 1 : 0)) * 128 + wc * 32 + 8 * fq;
;                 f32x4 v0 = acc[ai][bj][m][0] * rs, v1 = acc[ai][bj][m][1] * rs;
; #pragma unroll
;                 for (int j = 0; j < 4; ++j) { v0[j] = sigmoid_f(v0[j]); v1[j] = sigmoid_f(v1[j]); }
;                 u32x2 w; w.x = pk_unorm8(v0); w.y = pk_unorm8(v1);
;                 *(u32x2*)((unsigned char*)P + (size_t)row * ROWB + GATE_B0 + gcol) = w;
;             }
;         EPI_END
;     }
;     __device__ __forceinline__ void operator()(f32x4 (&acc)[2][2][4][2], const Unit& u, int wr, int wc, int fr, int fq) const {
;     ...
;         const int pn = u.pn + pn0;
;         if (pn < 8) body_pair<0>(acc, u, wr, wc, fr, fq, OQ + pn * 128, rsv);
;         else if (pn < 16) body_pair<1>(acc, u, wr, wc, fr, fq, OAB + (pn - 8) * 128, rsv);
;         else if (pn < 20) body<0>(acc, u, wr, wc, fr, fq, OBIN + (pn - 16) * 256, rsv);
;         else if (pn < 24) body<1>(acc, u, wr, wc, fr, fq, OBZ + (pn - 20) * 256, rsv);
;         else if (pn < 32) body_pair<2>(acc, u, wr, wc, fr, fq, OV + (pn - 24) * 128, rsv);
;         else if (pn < 36) body<1>(acc, u, wr, wc, fr, fq, OCZ + (pn - 32) * 256, rsv);
;         else body_gate(acc, u, wr, wc, fr, fq, (pn - 36) * 256, rsv);
.LBB0_200:
	s_cmp_gt_u32 s52, 15
	s_cbranch_scc0 .LBB0_218
	s_cmp_gt_u32 s52, 19
	s_cbranch_scc0 .LBB0_215
	s_cmp_gt_u32 s52, 23
	s_cbranch_scc0 .LBB0_212
	s_cmp_gt_u32 s52, 31
	s_cbranch_scc0 .LBB0_209
	v_mov_b32_e32 v159, v158
	v_pk_mul_f32 v[178:179], v[126:127], v[158:159] op_sel_hi:[1,0]
	s_lshl_b32 s6, s52, 8
	v_mul_f32_e32 v160, 0xbfb8aa3b, v178
	v_exp_f32_e32 v170, v160
	v_mad_i64_i32 v[168:169], s[4:5], v154, s33, 0
	v_pk_mul_f32 v[174:175], v[128:129], v[158:159] op_sel_hi:[1,0]
	v_add_f32_e32 v170, 1.0, v170
	v_rcp_f32_e32 v180, v170
	v_pk_mul_f32 v[160:161], v[124:125], v[158:159] op_sel_hi:[1,0]
	v_pk_mul_f32 v[176:177], v[122:123], v[158:159] op_sel_hi:[1,0]
	s_cmp_gt_u32 s52, 35
	v_lshlrev_b32_e32 v216, 3, v210
	s_mov_b64 s[4:5], -1
	v_lshl_add_u64 v[172:173], s[68:69], 0, v[168:169]
	v_mul_f32_e32 v218, 0xbfb8aa3b, v176
	v_mul_f32_e32 v217, 0xbfb8aa3b, v179
	v_mul_f32_e32 v215, 0xbfb8aa3b, v177
	v_mul_f32_e32 v214, 0xbfb8aa3b, v174
	v_mul_f32_e32 v213, 0xbfb8aa3b, v160
	v_mul_f32_e32 v212, 0xbfb8aa3b, v175
	v_mul_f32_e32 v211, 0xbfb8aa3b, v161
	v_pk_mul_f32 v[170:171], v[118:119], v[158:159]
	v_pk_mul_f32 v[168:169], v[110:111], v[158:159]
	s_cbranch_scc0 .LBB0_206
	s_mov_b32 s8, 0x437f0000
	s_add_i32 s4, s27, s6
	s_lshr_b32 s98, s4, 7
	s_and_b32 s98, s98, 14
	s_bfe_u32 s99, s4, 0x10006
	s_or_b32 s98, s98, s99
	v_sub_u32_e32 v230, s98, v1
	s_lshr_b32 s98, s4, 11
	s_lshl_b32 s98, s98, 11
	s_and_b32 s99, s4, 32
	s_lshl_b32 s99, s99, 4
	s_add_i32 s98, s98, s99
	s_addk_i32 s98, 0x3000
	v_lshl_add_u32 v228, v143, 7, s98
	v_lshl_add_u32 v228, v1, 3, v228
	v_mad_i32_i24 v228, v230, s33, v228
	v_ashrrev_i32_e32 v229, 31, v228
	v_lshl_add_u64 v[232:233], s[68:69], 0, v[228:229]
	v_mul_f32_e32 v158, 0xbfb8aa3b, v158
	v_mul_f32_e32 v156, 0xbfb8aa3b, v156
	v_mul_f32_e32 v152, 0xbfb8aa3b, v152
	v_mul_f32_e32 v150, 0xbfb8aa3b, v150
	v_mul_f32_e32 v148, 0xbfb8aa3b, v148
	v_mul_f32_e32 v146, 0xbfb8aa3b, v146
	v_mul_f32_e32 v144, 0xbfb8aa3b, v144
	v_mul_f32_e32 v142, 0xbfb8aa3b, v142
	v_mad_i64_i32 v[238:239], s[4:5], v154, s33, v[232:233]
	v_pk_mul_f32 v[126:127], v[126:127], v[158:159] op_sel_hi:[1,0]
	v_pk_mul_f32 v[128:129], v[128:129], v[158:159] op_sel_hi:[1,0]
	v_pk_mul_f32 v[122:123], v[122:123], v[158:159] op_sel_hi:[1,0]
	v_pk_mul_f32 v[124:125], v[124:125], v[158:159] op_sel_hi:[1,0]
	v_exp_f32_e32 v126, v126
	v_exp_f32_e32 v127, v127
	v_exp_f32_e32 v128, v128
	v_exp_f32_e32 v129, v129
	v_exp_f32_e32 v122, v122
	v_exp_f32_e32 v123, v123
	v_exp_f32_e32 v124, v124
	v_exp_f32_e32 v125, v125
	v_pk_add_f32 v[126:127], v[126:127], 1.0 op_sel_hi:[1,0]
	v_pk_add_f32 v[128:129], v[128:129], 1.0 op_sel_hi:[1,0]
	v_pk_add_f32 v[122:123], v[122:123], 1.0 op_sel_hi:[1,0]
	v_pk_add_f32 v[124:125], v[124:125], 1.0 op_sel_hi:[1,0]
	v_rcp_f32_e32 v126, v126
	v_rcp_f32_e32 v127, v127
	v_rcp_f32_e32 v128, v128
	v_rcp_f32_e32 v129, v129
	v_rcp_f32_e32 v122, v122
	v_rcp_f32_e32 v123, v123
	v_rcp_f32_e32 v124, v124
	v_rcp_f32_e32 v125, v125
	v_pk_fma_f32 v[126:127], v[126:127], s[8:9], 0.5 op_sel_hi:[1,0,0]
	v_pk_fma_f32 v[128:129], v[128:129], s[8:9], 0.5 op_sel_hi:[1,0,0]
	v_pk_fma_f32 v[122:123], v[122:123], s[8:9], 0.5 op_sel_hi:[1,0,0]
	v_pk_fma_f32 v[124:125], v[124:125], s[8:9], 0.5 op_sel_hi:[1,0,0]
	v_cvt_u32_f32_e32 v234, v126
	v_cvt_u32_f32_e32 v235, v122
	v_cvt_u32_f32_sdwa v234, v127 dst_sel:BYTE_1 dst_unused:UNUSED_PRESERVE src0_sel:DWORD
	v_cvt_u32_f32_sdwa v235, v123 dst_sel:BYTE_1 dst_unused:UNUSED_PRESERVE src0_sel:DWORD
	v_cvt_u32_f32_sdwa v234, v128 dst_sel:BYTE_2 dst_unused:UNUSED_PRESERVE src0_sel:DWORD
	v_cvt_u32_f32_sdwa v235, v124 dst_sel:BYTE_2 dst_unused:UNUSED_PRESERVE src0_sel:DWORD
	v_cvt_u32_f32_sdwa v234, v129 dst_sel:BYTE_3 dst_unused:UNUSED_PRESERVE src0_sel:DWORD
	v_cvt_u32_f32_sdwa v235, v125 dst_sel:BYTE_3 dst_unused:UNUSED_PRESERVE src0_sel:DWORD
	s_nop 1
	global_store_dwordx2 v[238:239], v[234:235], off nt
	v_pk_mul_f32 v[118:119], v[118:119], v[158:159] op_sel_hi:[1,0]
	v_pk_mul_f32 v[120:121], v[120:121], v[158:159] op_sel_hi:[1,0]
	v_pk_mul_f32 v[110:111], v[110:111], v[158:159] op_sel_hi:[1,0]
	v_pk_mul_f32 v[112:113], v[112:113], v[158:159] op_sel_hi:[1,0]
	v_exp_f32_e32 v118, v118
	v_exp_f32_e32 v119, v119
	v_exp_f32_e32 v120, v120
	v_exp_f32_e32 v121, v121
	v_exp_f32_e32 v110, v110
	v_exp_f32_e32 v111, v111
	v_exp_f32_e32 v112, v112
	v_exp_f32_e32 v113, v113
	v_pk_add_f32 v[118:119], v[118:119], 1.0 op_sel_hi:[1,0]
	v_pk_add_f32 v[120:121], v[120:121], 1.0 op_sel_hi:[1,0]
	v_pk_add_f32 v[110:111], v[110:111], 1.0 op_sel_hi:[1,0]
	v_pk_add_f32 v[112:113], v[112:113], 1.0 op_sel_hi:[1,0]
	v_rcp_f32_e32 v118, v118
	v_rcp_f32_e32 v119, v119
	v_rcp_f32_e32 v120, v120
	v_rcp_f32_e32 v121, v121
	v_rcp_f32_e32 v110, v110
	v_rcp_f32_e32 v111, v111
	v_rcp_f32_e32 v112, v112
	v_rcp_f32_e32 v113, v113
	v_pk_fma_f32 v[118:119], v[118:119], s[8:9], 0.5 op_sel_hi:[1,0,0]
	v_pk_fma_f32 v[120:121], v[120:121], s[8:9], 0.5 op_sel_hi:[1,0,0]
	v_pk_fma_f32 v[110:111], v[110:111], s[8:9], 0.5 op_sel_hi:[1,0,0]
	v_pk_fma_f32 v[112:113], v[112:113], s[8:9], 0.5 op_sel_hi:[1,0,0]
	v_cvt_u32_f32_e32 v236, v118
	v_cvt_u32_f32_e32 v237, v110
	v_cvt_u32_f32_sdwa v236, v119 dst_sel:BYTE_1 dst_unused:UNUSED_PRESERVE src0_sel:DWORD
	v_cvt_u32_f32_sdwa v237, v111 dst_sel:BYTE_1 dst_unused:UNUSED_PRESERVE src0_sel:DWORD
	v_cvt_u32_f32_sdwa v236, v120 dst_sel:BYTE_2 dst_unused:UNUSED_PRESERVE src0_sel:DWORD
	v_cvt_u32_f32_sdwa v237, v112 dst_sel:BYTE_2 dst_unused:UNUSED_PRESERVE src0_sel:DWORD
	v_cvt_u32_f32_sdwa v236, v121 dst_sel:BYTE_3 dst_unused:UNUSED_PRESERVE src0_sel:DWORD
	v_cvt_u32_f32_sdwa v237, v113 dst_sel:BYTE_3 dst_unused:UNUSED_PRESERVE src0_sel:DWORD
; __device__ __forceinline__ float sigmoid_f(float x) { return __builtin_amdgcn_rcpf(1.0f + __builtin_amdgcn_exp2f(-1.4426950409f * x)); }
;     __device__ __forceinline__ void body_gate(f32x4 (&acc)[2][2][4][2], const Unit& u, int wr, int wc, int fr, int fq, int gbase, const float (&rsv)[2][4]) const {
;         EPI_ROWS_BEGIN
;             const float rs = rsv[ai][m];
; #pragma unroll
;             for (int bj = 0; bj < 2; ++bj) { if (u.half != 0 && bj == 1) continue;
;                 const int gcol = gbase + (bj + (u.half == 2 ? 1 : 0)) * 128 + wc * 32 + 8 * fq;
;                 f32x4 v0 = acc[ai][bj][m][0] * rs, v1 = acc[ai][bj][m][1] * rs;
; #pragma unroll
;                 for (int j = 0; j < 4; ++j) { v0[j] = sigmoid_f(v0[j]); v1[j] = sigmoid_f(v1[j]); }
;                 u32x2 w; w.x = pk_unorm8(v0); w.y = pk_unorm8(v1);
;                 *(u32x2*)((unsigned char*)P + (size_t)row * ROWB + GATE_B0 + gcol) = w;
;             }
;         EPI_END
;     }
	s_nop 1
	global_store_dwordx2 v[238:239], v[236:237], off offset:1024 nt
	v_mad_i64_i32 v[240:241], s[4:5], v209, s33, v[232:233]
	v_pk_mul_f32 v[114:115], v[114:115], v[156:157] op_sel_hi:[1,0]
	v_pk_mul_f32 v[116:117], v[116:117], v[156:157] op_sel_hi:[1,0]
	v_pk_mul_f32 v[106:107], v[106:107], v[156:157] op_sel_hi:[1,0]
	v_pk_mul_f32 v[108:109], v[108:109], v[156:157] op_sel_hi:[1,0]
	v_exp_f32_e32 v114, v114
	v_exp_f32_e32 v115, v115
	v_exp_f32_e32 v116, v116
	v_exp_f32_e32 v117, v117
	v_exp_f32_e32 v106, v106
	v_exp_f32_e32 v107, v107
	v_exp_f32_e32 v108, v108
	v_exp_f32_e32 v109, v109
	v_pk_add_f32 v[114:115], v[114:115], 1.0 op_sel_hi:[1,0]
	v_pk_add_f32 v[116:117], v[116:117], 1.0 op_sel_hi:[1,0]
	v_pk_add_f32 v[106:107], v[106:107], 1.0 op_sel_hi:[1,0]
	v_pk_add_f32 v[108:109], v[108:109], 1.0 op_sel_hi:[1,0]
	v_rcp_f32_e32 v114, v114
	v_rcp_f32_e32 v115, v115
	v_rcp_f32_e32 v116, v116
	v_rcp_f32_e32 v117, v117
	v_rcp_f32_e32 v106, v106
	v_rcp_f32_e32 v107, v107
	v_rcp_f32_e32 v108, v108
	v_rcp_f32_e32 v109, v109
	v_pk_fma_f32 v[114:115], v[114:115], s[8:9], 0.5 op_sel_hi:[1,0,0]
	v_pk_fma_f32 v[116:117], v[116:117], s[8:9], 0.5 op_sel_hi:[1,0,0]
	v_pk_fma_f32 v[106:107], v[106:107], s[8:9], 0.5 op_sel_hi:[1,0,0]
	v_pk_fma_f32 v[108:109], v[108:109], s[8:9], 0.5 op_sel_hi:[1,0,0]
	v_cvt_u32_f32_e32 v234, v114
	v_cvt_u32_f32_e32 v235, v106
	v_cvt_u32_f32_sdwa v234, v115 dst_sel:BYTE_1 dst_unused:UNUSED_PRESERVE src0_sel:DWORD
	v_cvt_u32_f32_sdwa v235, v107 dst_sel:BYTE_1 dst_unused:UNUSED_PRESERVE src0_sel:DWORD
	v_cvt_u32_f32_sdwa v234, v116 dst_sel:BYTE_2 dst_unused:UNUSED_PRESERVE src0_sel:DWORD
	v_cvt_u32_f32_sdwa v235, v108 dst_sel:BYTE_2 dst_unused:UNUSED_PRESERVE src0_sel:DWORD
	v_cvt_u32_f32_sdwa v234, v117 dst_sel:BYTE_3 dst_unused:UNUSED_PRESERVE src0_sel:DWORD
	v_cvt_u32_f32_sdwa v235, v109 dst_sel:BYTE_3 dst_unused:UNUSED_PRESERVE src0_sel:DWORD
	s_nop 1
	global_store_dwordx2 v[240:241], v[234:235], off nt
	v_pk_mul_f32 v[98:99], v[98:99], v[156:157] op_sel_hi:[1,0]
	v_pk_mul_f32 v[100:101], v[100:101], v[156:157] op_sel_hi:[1,0]
	v_pk_mul_f32 v[90:91], v[90:91], v[156:157] op_sel_hi:[1,0]
	v_pk_mul_f32 v[92:93], v[92:93], v[156:157] op_sel_hi:[1,0]
	v_exp_f32_e32 v98, v98
	v_exp_f32_e32 v99, v99
	v_exp_f32_e32 v100, v100
	v_exp_f32_e32 v101, v101
	v_exp_f32_e32 v90, v90
	v_exp_f32_e32 v91, v91
	v_exp_f32_e32 v92, v92
	v_exp_f32_e32 v93, v93
	v_pk_add_f32 v[98:99], v[98:99], 1.0 op_sel_hi:[1,0]
	v_pk_add_f32 v[100:101], v[100:101], 1.0 op_sel_hi:[1,0]
	v_pk_add_f32 v[90:91], v[90:91], 1.0 op_sel_hi:[1,0]
	v_pk_add_f32 v[92:93], v[92:93], 1.0 op_sel_hi:[1,0]
	v_rcp_f32_e32 v98, v98
	v_rcp_f32_e32 v99, v99
	v_rcp_f32_e32 v100, v100
	v_rcp_f32_e32 v101, v101
	v_rcp_f32_e32 v90, v90
	v_rcp_f32_e32 v91, v91
	v_rcp_f32_e32 v92, v92
	v_rcp_f32_e32 v93, v93
	v_pk_fma_f32 v[98:99], v[98:99], s[8:9], 0.5 op_sel_hi:[1,0,0]
	v_pk_fma_f32 v[100:101], v[100:101], s[8:9], 0.5 op_sel_hi:[1,0,0]
	v_pk_fma_f32 v[90:91], v[90:91], s[8:9], 0.5 op_sel_hi:[1,0,0]
	v_pk_fma_f32 v[92:93], v[92:93], s[8:9], 0.5 op_sel_hi:[1,0,0]
	v_cvt_u32_f32_e32 v236, v98
	v_cvt_u32_f32_e32 v237, v90
	v_cvt_u32_f32_sdwa v236, v99 dst_sel:BYTE_1 dst_unused:UNUSED_PRESERVE src0_sel:DWORD
	v_cvt_u32_f32_sdwa v237, v91 dst_sel:BYTE_1 dst_unused:UNUSED_PRESERVE src0_sel:DWORD
	v_cvt_u32_f32_sdwa v236, v100 dst_sel:BYTE_2 dst_unused:UNUSED_PRESERVE src0_sel:DWORD
	v_cvt_u32_f32_sdwa v237, v92 dst_sel:BYTE_2 dst_unused:UNUSED_PRESERVE src0_sel:DWORD
	v_cvt_u32_f32_sdwa v236, v101 dst_sel:BYTE_3 dst_unused:UNUSED_PRESERVE src0_sel:DWORD
	v_cvt_u32_f32_sdwa v237, v93 dst_sel:BYTE_3 dst_unused:UNUSED_PRESERVE src0_sel:DWORD
	s_nop 1
	global_store_dwordx2 v[240:241], v[236:237], off offset:1024 nt
	v_mad_i64_i32 v[238:239], s[4:5], v208, s33, v[232:233]
	v_pk_mul_f32 v[102:103], v[102:103], v[152:153] op_sel_hi:[1,0]
	v_pk_mul_f32 v[104:105], v[104:105], v[152:153] op_sel_hi:[1,0]
	v_pk_mul_f32 v[94:95], v[94:95], v[152:153] op_sel_hi:[1,0]
	v_pk_mul_f32 v[96:97], v[96:97], v[152:153] op_sel_hi:[1,0]
	v_exp_f32_e32 v102, v102
	v_exp_f32_e32 v103, v103
	v_exp_f32_e32 v104, v104
	v_exp_f32_e32 v105, v105
	v_exp_f32_e32 v94, v94
	v_exp_f32_e32 v95, v95
	v_exp_f32_e32 v96, v96
	v_exp_f32_e32 v97, v97
	v_pk_add_f32 v[102:103], v[102:103], 1.0 op_sel_hi:[1,0]
	v_pk_add_f32 v[104:105], v[104:105], 1.0 op_sel_hi:[1,0]
	v_pk_add_f32 v[94:95], v[94:95], 1.0 op_sel_hi:[1,0]
	v_pk_add_f32 v[96:97], v[96:97], 1.0 op_sel_hi:[1,0]
	v_rcp_f32_e32 v102, v102
	v_rcp_f32_e32 v103, v103
	v_rcp_f32_e32 v104, v104
	v_rcp_f32_e32 v105, v105
	v_rcp_f32_e32 v94, v94
	v_rcp_f32_e32 v95, v95
	v_rcp_f32_e32 v96, v96
	v_rcp_f32_e32 v97, v97
	v_pk_fma_f32 v[102:103], v[102:103], s[8:9], 0.5 op_sel_hi:[1,0,0]
	v_pk_fma_f32 v[104:105], v[104:105], s[8:9], 0.5 op_sel_hi:[1,0,0]
	v_pk_fma_f32 v[94:95], v[94:95], s[8:9], 0.5 op_sel_hi:[1,0,0]
	v_pk_fma_f32 v[96:97], v[96:97], s[8:9], 0.5 op_sel_hi:[1,0,0]
	v_cvt_u32_f32_e32 v234, v102
	v_cvt_u32_f32_e32 v235, v94
	v_cvt_u32_f32_sdwa v234, v103 dst_sel:BYTE_1 dst_unused:UNUSED_PRESERVE src0_sel:DWORD
	v_cvt_u32_f32_sdwa v235, v95 dst_sel:BYTE_1 dst_unused:UNUSED_PRESERVE src0_sel:DWORD
	v_cvt_u32_f32_sdwa v234, v104 dst_sel:BYTE_2 dst_unused:UNUSED_PRESERVE src0_sel:DWORD
	v_cvt_u32_f32_sdwa v235, v96 dst_sel:BYTE_2 dst_unused:UNUSED_PRESERVE src0_sel:DWORD
	v_cvt_u32_f32_sdwa v234, v105 dst_sel:BYTE_3 dst_unused:UNUSED_PRESERVE src0_sel:DWORD
	v_cvt_u32_f32_sdwa v235, v97 dst_sel:BYTE_3 dst_unused:UNUSED_PRESERVE src0_sel:DWORD
	s_nop 1
	global_store_dwordx2 v[238:239], v[234:235], off nt
	v_pk_mul_f32 v[82:83], v[82:83], v[152:153] op_sel_hi:[1,0]
; __device__ __forceinline__ unsigned cvt_pk_bf16(float lo, float hi) { const bf16x2_t r = __builtin_convertvector((f32x2){lo, hi}, bf16x2_t); return __builtin_bit_cast(unsigned, r); }
; __device__ __forceinline__ float bf_lo(unsigned u) { return __uint_as_float(u << 16); }
; __device__ __forceinline__ float bf_hi(unsigned u) { return __uint_as_float(u & 0xffff0000u); }
; __device__ __forceinline__ float sigmoid_f(float x) { return __builtin_amdgcn_rcpf(1.0f + __builtin_amdgcn_exp2f(-1.4426950409f * x)); }
; __device__ __forceinline__ float silu_f(float x) { return x * sigmoid_f(x); }
; __device__ __forceinline__ u32x4 pack8(f32x4 a, f32x4 b) { u32x4 w; w.x = cvt_pk_bf16(a[0], a[1]); w.y = cvt_pk_bf16(a[2], a[3]); w.z = cvt_pk_bf16(b[0], b[1]); w.w = cvt_pk_bf16(b[2], b[3]); return w; }
; __device__ __forceinline__ void unpack8(u32x4 g, f32x4& a, f32x4& b) { a = (f32x4){bf_lo(g.x), bf_hi(g.x), bf_lo(g.y), bf_hi(g.y)}; b = (f32x4){bf_lo(g.z), bf_hi(g.z), bf_lo(g.w), bf_hi(g.w)}; }
;     __device__ __forceinline__ void body_gate(f32x4 (&acc)[2][2][4][2], const Unit& u, int wr, int wc, int fr, int fq, int gbase, const float (&rsv)[2][4]) const {
;     ...
;             const float rs = rsv[ai][m];
; #pragma unroll
;             for (int bj = 0; bj < 2; ++bj) { if (u.half != 0 && bj == 1) continue;
;                 const int gcol = gbase + (bj + (u.half == 2 ? 1 : 0)) * 128 + wc * 32 + 8 * fq;
;                 f32x4 v0 = acc[ai][bj][m][0] * rs, v1 = acc[ai][bj][m][1] * rs;
; #pragma unroll
;                 for (int j = 0; j < 4; ++j) { v0[j] = sigmoid_f(v0[j]); v1[j] = sigmoid_f(v1[j]); }
;                 u32x2 w; w.x = pk_unorm8(v0); w.y = pk_unorm8(v1);
;                 *(u32x2*)((unsigned char*)P + (size_t)row * ROWB + GATE_B0 + gcol) = w;
	v_pk_mul_f32 v[84:85], v[84:85], v[152:153] op_sel_hi:[1,0]
	v_pk_mul_f32 v[74:75], v[74:75], v[152:153] op_sel_hi:[1,0]
	v_pk_mul_f32 v[76:77], v[76:77], v[152:153] op_sel_hi:[1,0]
	v_exp_f32_e32 v82, v82
	v_exp_f32_e32 v83, v83
	v_exp_f32_e32 v84, v84
	v_exp_f32_e32 v85, v85
	v_exp_f32_e32 v74, v74
	v_exp_f32_e32 v75, v75
	v_exp_f32_e32 v76, v76
	v_exp_f32_e32 v77, v77
	v_pk_add_f32 v[82:83], v[82:83], 1.0 op_sel_hi:[1,0]
	v_pk_add_f32 v[84:85], v[84:85], 1.0 op_sel_hi:[1,0]
	v_pk_add_f32 v[74:75], v[74:75], 1.0 op_sel_hi:[1,0]
	v_pk_add_f32 v[76:77], v[76:77], 1.0 op_sel_hi:[1,0]
	v_rcp_f32_e32 v82, v82
	v_rcp_f32_e32 v83, v83
	v_rcp_f32_e32 v84, v84
	v_rcp_f32_e32 v85, v85
	v_rcp_f32_e32 v74, v74
	v_rcp_f32_e32 v75, v75
	v_rcp_f32_e32 v76, v76
	v_rcp_f32_e32 v77, v77
	v_pk_fma_f32 v[82:83], v[82:83], s[8:9], 0.5 op_sel_hi:[1,0,0]
	v_pk_fma_f32 v[84:85], v[84:85], s[8:9], 0.5 op_sel_hi:[1,0,0]
	v_pk_fma_f32 v[74:75], v[74:75], s[8:9], 0.5 op_sel_hi:[1,0,0]
	v_pk_fma_f32 v[76:77], v[76:77], s[8:9], 0.5 op_sel_hi:[1,0,0]
	v_cvt_u32_f32_e32 v236, v82
	v_cvt_u32_f32_e32 v237, v74
	v_cvt_u32_f32_sdwa v236, v83 dst_sel:BYTE_1 dst_unused:UNUSED_PRESERVE src0_sel:DWORD
	v_cvt_u32_f32_sdwa v237, v75 dst_sel:BYTE_1 dst_unused:UNUSED_PRESERVE src0_sel:DWORD
	v_cvt_u32_f32_sdwa v236, v84 dst_sel:BYTE_2 dst_unused:UNUSED_PRESERVE src0_sel:DWORD
	v_cvt_u32_f32_sdwa v237, v76 dst_sel:BYTE_2 dst_unused:UNUSED_PRESERVE src0_sel:DWORD
	v_cvt_u32_f32_sdwa v236, v85 dst_sel:BYTE_3 dst_unused:UNUSED_PRESERVE src0_sel:DWORD
	v_cvt_u32_f32_sdwa v237, v77 dst_sel:BYTE_3 dst_unused:UNUSED_PRESERVE src0_sel:DWORD
	s_nop 1
	global_store_dwordx2 v[238:239], v[236:237], off offset:1024 nt
	v_mad_i64_i32 v[240:241], s[4:5], v157, s33, v[232:233]
	v_pk_mul_f32 v[86:87], v[86:87], v[150:151] op_sel_hi:[1,0]
	v_pk_mul_f32 v[88:89], v[88:89], v[150:151] op_sel_hi:[1,0]
	v_pk_mul_f32 v[78:79], v[78:79], v[150:151] op_sel_hi:[1,0]
	v_pk_mul_f32 v[80:81], v[80:81], v[150:151] op_sel_hi:[1,0]
	v_exp_f32_e32 v86, v86
	v_exp_f32_e32 v87, v87
	v_exp_f32_e32 v88, v88
	v_exp_f32_e32 v89, v89
	v_exp_f32_e32 v78, v78
	v_exp_f32_e32 v79, v79
	v_exp_f32_e32 v80, v80
	v_exp_f32_e32 v81, v81
	v_pk_add_f32 v[86:87], v[86:87], 1.0 op_sel_hi:[1,0]
	v_pk_add_f32 v[88:89], v[88:89], 1.0 op_sel_hi:[1,0]
	v_pk_add_f32 v[78:79], v[78:79], 1.0 op_sel_hi:[1,0]
	v_pk_add_f32 v[80:81], v[80:81], 1.0 op_sel_hi:[1,0]
	v_rcp_f32_e32 v86, v86
	v_rcp_f32_e32 v87, v87
	v_rcp_f32_e32 v88, v88
	v_rcp_f32_e32 v89, v89
	v_rcp_f32_e32 v78, v78
	v_rcp_f32_e32 v79, v79
	v_rcp_f32_e32 v80, v80
	v_rcp_f32_e32 v81, v81
	v_pk_fma_f32 v[86:87], v[86:87], s[8:9], 0.5 op_sel_hi:[1,0,0]
	v_pk_fma_f32 v[88:89], v[88:89], s[8:9], 0.5 op_sel_hi:[1,0,0]
	v_pk_fma_f32 v[78:79], v[78:79], s[8:9], 0.5 op_sel_hi:[1,0,0]
	v_pk_fma_f32 v[80:81], v[80:81], s[8:9], 0.5 op_sel_hi:[1,0,0]
	v_cvt_u32_f32_e32 v234, v86
	v_cvt_u32_f32_e32 v235, v78
	v_cvt_u32_f32_sdwa v234, v87 dst_sel:BYTE_1 dst_unused:UNUSED_PRESERVE src0_sel:DWORD
	v_cvt_u32_f32_sdwa v235, v79 dst_sel:BYTE_1 dst_unused:UNUSED_PRESERVE src0_sel:DWORD
	v_cvt_u32_f32_sdwa v234, v88 dst_sel:BYTE_2 dst_unused:UNUSED_PRESERVE src0_sel:DWORD
	v_cvt_u32_f32_sdwa v235, v80 dst_sel:BYTE_2 dst_unused:UNUSED_PRESERVE src0_sel:DWORD
	v_cvt_u32_f32_sdwa v234, v89 dst_sel:BYTE_3 dst_unused:UNUSED_PRESERVE src0_sel:DWORD
	v_cvt_u32_f32_sdwa v235, v81 dst_sel:BYTE_3 dst_unused:UNUSED_PRESERVE src0_sel:DWORD
	s_nop 1
	global_store_dwordx2 v[240:241], v[234:235], off nt
	v_pk_mul_f32 v[70:71], v[70:71], v[150:151] op_sel_hi:[1,0]
	v_pk_mul_f32 v[72:73], v[72:73], v[150:151] op_sel_hi:[1,0]
	v_pk_mul_f32 v[66:67], v[66:67], v[150:151] op_sel_hi:[1,0]
	v_pk_mul_f32 v[68:69], v[68:69], v[150:151] op_sel_hi:[1,0]
	v_exp_f32_e32 v70, v70
	v_exp_f32_e32 v71, v71
	v_exp_f32_e32 v72, v72
	v_exp_f32_e32 v73, v73
	v_exp_f32_e32 v66, v66
	v_exp_f32_e32 v67, v67
	v_exp_f32_e32 v68, v68
	v_exp_f32_e32 v69, v69
	v_pk_add_f32 v[70:71], v[70:71], 1.0 op_sel_hi:[1,0]
	v_pk_add_f32 v[72:73], v[72:73], 1.0 op_sel_hi:[1,0]
	v_pk_add_f32 v[66:67], v[66:67], 1.0 op_sel_hi:[1,0]
	v_pk_add_f32 v[68:69], v[68:69], 1.0 op_sel_hi:[1,0]
	v_rcp_f32_e32 v70, v70
	v_rcp_f32_e32 v71, v71
	v_rcp_f32_e32 v72, v72
	v_rcp_f32_e32 v73, v73
	v_rcp_f32_e32 v66, v66
	v_rcp_f32_e32 v67, v67
	v_rcp_f32_e32 v68, v68
	v_rcp_f32_e32 v69, v69
	v_pk_fma_f32 v[70:71], v[70:71], s[8:9], 0.5 op_sel_hi:[1,0,0]
	v_pk_fma_f32 v[72:73], v[72:73], s[8:9], 0.5 op_sel_hi:[1,0,0]
	v_pk_fma_f32 v[66:67], v[66:67], s[8:9], 0.5 op_sel_hi:[1,0,0]
	v_pk_fma_f32 v[68:69], v[68:69], s[8:9], 0.5 op_sel_hi:[1,0,0]
	v_cvt_u32_f32_e32 v236, v70
	v_cvt_u32_f32_e32 v237, v66
	v_cvt_u32_f32_sdwa v236, v71 dst_sel:BYTE_1 dst_unused:UNUSED_PRESERVE src0_sel:DWORD
	v_cvt_u32_f32_sdwa v237, v67 dst_sel:BYTE_1 dst_unused:UNUSED_PRESERVE src0_sel:DWORD
	v_cvt_u32_f32_sdwa v236, v72 dst_sel:BYTE_2 dst_unused:UNUSED_PRESERVE src0_sel:DWORD
	v_cvt_u32_f32_sdwa v237, v68 dst_sel:BYTE_2 dst_unused:UNUSED_PRESERVE src0_sel:DWORD
	v_cvt_u32_f32_sdwa v236, v73 dst_sel:BYTE_3 dst_unused:UNUSED_PRESERVE src0_sel:DWORD
	v_cvt_u32_f32_sdwa v237, v69 dst_sel:BYTE_3 dst_unused:UNUSED_PRESERVE src0_sel:DWORD
	s_nop 1
	global_store_dwordx2 v[240:241], v[236:237], off offset:1024 nt
	v_mad_i64_i32 v[238:239], s[4:5], v155, s33, v[232:233]
	v_pk_mul_f32 v[62:63], v[62:63], v[148:149] op_sel_hi:[1,0]
	v_pk_mul_f32 v[64:65], v[64:65], v[148:149] op_sel_hi:[1,0]
	v_pk_mul_f32 v[58:59], v[58:59], v[148:149] op_sel_hi:[1,0]
	v_pk_mul_f32 v[60:61], v[60:61], v[148:149] op_sel_hi:[1,0]
	v_exp_f32_e32 v62, v62
	v_exp_f32_e32 v63, v63
	v_exp_f32_e32 v64, v64
	v_exp_f32_e32 v65, v65
; __device__ __forceinline__ unsigned cvt_pk_bf16(float lo, float hi) { const bf16x2_t r = __builtin_convertvector((f32x2){lo, hi}, bf16x2_t); return __builtin_bit_cast(unsigned, r); }
; __device__ __forceinline__ float bf_lo(unsigned u) { return __uint_as_float(u << 16); }
; __device__ __forceinline__ float bf_hi(unsigned u) { return __uint_as_float(u & 0xffff0000u); }
; __device__ __forceinline__ float sigmoid_f(float x) { return __builtin_amdgcn_rcpf(1.0f + __builtin_amdgcn_exp2f(-1.4426950409f * x)); }
; __device__ __forceinline__ float silu_f(float x) { return x * sigmoid_f(x); }
; __device__ __forceinline__ u32x4 pack8(f32x4 a, f32x4 b) { u32x4 w; w.x = cvt_pk_bf16(a[0], a[1]); w.y = cvt_pk_bf16(a[2], a[3]); w.z = cvt_pk_bf16(b[0], b[1]); w.w = cvt_pk_bf16(b[2], b[3]); return w; }
; __device__ __forceinline__ void unpack8(u32x4 g, f32x4& a, f32x4& b) { a = (f32x4){bf_lo(g.x), bf_hi(g.x), bf_lo(g.y), bf_hi(g.y)}; b = (f32x4){bf_lo(g.z), bf_hi(g.z), bf_lo(g.w), bf_hi(g.w)}; }
;     __device__ __forceinline__ void body_gate(f32x4 (&acc)[2][2][4][2], const Unit& u, int wr, int wc, int fr, int fq, int gbase, const float (&rsv)[2][4]) const {
;     ...
;             const float rs = rsv[ai][m];
; #pragma unroll
;             for (int bj = 0; bj < 2; ++bj) { if (u.half != 0 && bj == 1) continue;
;                 const int gcol = gbase + (bj + (u.half == 2 ? 1 : 0)) * 128 + wc * 32 + 8 * fq;
;                 f32x4 v0 = acc[ai][bj][m][0] * rs, v1 = acc[ai][bj][m][1] * rs;
; #pragma unroll
;                 for (int j = 0; j < 4; ++j) { v0[j] = sigmoid_f(v0[j]); v1[j] = sigmoid_f(v1[j]); }
;                 u32x2 w; w.x = pk_unorm8(v0); w.y = pk_unorm8(v1);
;                 *(u32x2*)((unsigned char*)P + (size_t)row * ROWB + GATE_B0 + gcol) = w;
	v_exp_f32_e32 v58, v58
	v_exp_f32_e32 v59, v59
	v_exp_f32_e32 v60, v60
	v_exp_f32_e32 v61, v61
	v_pk_add_f32 v[62:63], v[62:63], 1.0 op_sel_hi:[1,0]
	v_pk_add_f32 v[64:65], v[64:65], 1.0 op_sel_hi:[1,0]
	v_pk_add_f32 v[58:59], v[58:59], 1.0 op_sel_hi:[1,0]
	v_pk_add_f32 v[60:61], v[60:61], 1.0 op_sel_hi:[1,0]
	v_rcp_f32_e32 v62, v62
	v_rcp_f32_e32 v63, v63
	v_rcp_f32_e32 v64, v64
	v_rcp_f32_e32 v65, v65
	v_rcp_f32_e32 v58, v58
	v_rcp_f32_e32 v59, v59
	v_rcp_f32_e32 v60, v60
	v_rcp_f32_e32 v61, v61
	v_pk_fma_f32 v[62:63], v[62:63], s[8:9], 0.5 op_sel_hi:[1,0,0]
	v_pk_fma_f32 v[64:65], v[64:65], s[8:9], 0.5 op_sel_hi:[1,0,0]
	v_pk_fma_f32 v[58:59], v[58:59], s[8:9], 0.5 op_sel_hi:[1,0,0]
	v_pk_fma_f32 v[60:61], v[60:61], s[8:9], 0.5 op_sel_hi:[1,0,0]
	v_cvt_u32_f32_e32 v234, v62
	v_cvt_u32_f32_e32 v235, v58
	v_cvt_u32_f32_sdwa v234, v63 dst_sel:BYTE_1 dst_unused:UNUSED_PRESERVE src0_sel:DWORD
	v_cvt_u32_f32_sdwa v235, v59 dst_sel:BYTE_1 dst_unused:UNUSED_PRESERVE src0_sel:DWORD
	v_cvt_u32_f32_sdwa v234, v64 dst_sel:BYTE_2 dst_unused:UNUSED_PRESERVE src0_sel:DWORD
	v_cvt_u32_f32_sdwa v235, v60 dst_sel:BYTE_2 dst_unused:UNUSED_PRESERVE src0_sel:DWORD
	v_cvt_u32_f32_sdwa v234, v65 dst_sel:BYTE_3 dst_unused:UNUSED_PRESERVE src0_sel:DWORD
	v_cvt_u32_f32_sdwa v235, v61 dst_sel:BYTE_3 dst_unused:UNUSED_PRESERVE src0_sel:DWORD
	s_nop 1
	global_store_dwordx2 v[238:239], v[234:235], off nt
	v_pk_mul_f32 v[50:51], v[50:51], v[148:149] op_sel_hi:[1,0]
	v_pk_mul_f32 v[52:53], v[52:53], v[148:149] op_sel_hi:[1,0]
	v_pk_mul_f32 v[42:43], v[42:43], v[148:149] op_sel_hi:[1,0]
	v_pk_mul_f32 v[44:45], v[44:45], v[148:149] op_sel_hi:[1,0]
	v_exp_f32_e32 v50, v50
	v_exp_f32_e32 v51, v51
	v_exp_f32_e32 v52, v52
	v_exp_f32_e32 v53, v53
	v_exp_f32_e32 v42, v42
	v_exp_f32_e32 v43, v43
	v_exp_f32_e32 v44, v44
	v_exp_f32_e32 v45, v45
	v_pk_add_f32 v[50:51], v[50:51], 1.0 op_sel_hi:[1,0]
	v_pk_add_f32 v[52:53], v[52:53], 1.0 op_sel_hi:[1,0]
	v_pk_add_f32 v[42:43], v[42:43], 1.0 op_sel_hi:[1,0]
	v_pk_add_f32 v[44:45], v[44:45], 1.0 op_sel_hi:[1,0]
	v_rcp_f32_e32 v50, v50
	v_rcp_f32_e32 v51, v51
	v_rcp_f32_e32 v52, v52
	v_rcp_f32_e32 v53, v53
	v_rcp_f32_e32 v42, v42
	v_rcp_f32_e32 v43, v43
	v_rcp_f32_e32 v44, v44
	v_rcp_f32_e32 v45, v45
	v_pk_fma_f32 v[50:51], v[50:51], s[8:9], 0.5 op_sel_hi:[1,0,0]
	v_pk_fma_f32 v[52:53], v[52:53], s[8:9], 0.5 op_sel_hi:[1,0,0]
	v_pk_fma_f32 v[42:43], v[42:43], s[8:9], 0.5 op_sel_hi:[1,0,0]
	v_pk_fma_f32 v[44:45], v[44:45], s[8:9], 0.5 op_sel_hi:[1,0,0]
	v_cvt_u32_f32_e32 v236, v50
	v_cvt_u32_f32_e32 v237, v42
	v_cvt_u32_f32_sdwa v236, v51 dst_sel:BYTE_1 dst_unused:UNUSED_PRESERVE src0_sel:DWORD
	v_cvt_u32_f32_sdwa v237, v43 dst_sel:BYTE_1 dst_unused:UNUSED_PRESERVE src0_sel:DWORD
	v_cvt_u32_f32_sdwa v236, v52 dst_sel:BYTE_2 dst_unused:UNUSED_PRESERVE src0_sel:DWORD
	v_cvt_u32_f32_sdwa v237, v44 dst_sel:BYTE_2 dst_unused:UNUSED_PRESERVE src0_sel:DWORD
	v_cvt_u32_f32_sdwa v236, v53 dst_sel:BYTE_3 dst_unused:UNUSED_PRESERVE src0_sel:DWORD
	v_cvt_u32_f32_sdwa v237, v45 dst_sel:BYTE_3 dst_unused:UNUSED_PRESERVE src0_sel:DWORD
	s_nop 1
	global_store_dwordx2 v[238:239], v[236:237], off offset:1024 nt
	v_mad_i64_i32 v[240:241], s[4:5], v153, s33, v[232:233]
	v_pk_mul_f32 v[54:55], v[54:55], v[146:147] op_sel_hi:[1,0]
	v_pk_mul_f32 v[56:57], v[56:57], v[146:147] op_sel_hi:[1,0]
	v_pk_mul_f32 v[46:47], v[46:47], v[146:147] op_sel_hi:[1,0]
	v_pk_mul_f32 v[48:49], v[48:49], v[146:147] op_sel_hi:[1,0]
	v_exp_f32_e32 v54, v54
	v_exp_f32_e32 v55, v55
	v_exp_f32_e32 v56, v56
	v_exp_f32_e32 v57, v57
	v_exp_f32_e32 v46, v46
	v_exp_f32_e32 v47, v47
	v_exp_f32_e32 v48, v48
	v_exp_f32_e32 v49, v49
	v_pk_add_f32 v[54:55], v[54:55], 1.0 op_sel_hi:[1,0]
	v_pk_add_f32 v[56:57], v[56:57], 1.0 op_sel_hi:[1,0]
	v_pk_add_f32 v[46:47], v[46:47], 1.0 op_sel_hi:[1,0]
	v_pk_add_f32 v[48:49], v[48:49], 1.0 op_sel_hi:[1,0]
	v_rcp_f32_e32 v54, v54
	v_rcp_f32_e32 v55, v55
	v_rcp_f32_e32 v56, v56
	v_rcp_f32_e32 v57, v57
	v_rcp_f32_e32 v46, v46
	v_rcp_f32_e32 v47, v47
	v_rcp_f32_e32 v48, v48
	v_rcp_f32_e32 v49, v49
	v_pk_fma_f32 v[54:55], v[54:55], s[8:9], 0.5 op_sel_hi:[1,0,0]
	v_pk_fma_f32 v[56:57], v[56:57], s[8:9], 0.5 op_sel_hi:[1,0,0]
	v_pk_fma_f32 v[46:47], v[46:47], s[8:9], 0.5 op_sel_hi:[1,0,0]
	v_pk_fma_f32 v[48:49], v[48:49], s[8:9], 0.5 op_sel_hi:[1,0,0]
	v_cvt_u32_f32_e32 v234, v54
	v_cvt_u32_f32_e32 v235, v46
	v_cvt_u32_f32_sdwa v234, v55 dst_sel:BYTE_1 dst_unused:UNUSED_PRESERVE src0_sel:DWORD
	v_cvt_u32_f32_sdwa v235, v47 dst_sel:BYTE_1 dst_unused:UNUSED_PRESERVE src0_sel:DWORD
	v_cvt_u32_f32_sdwa v234, v56 dst_sel:BYTE_2 dst_unused:UNUSED_PRESERVE src0_sel:DWORD
	v_cvt_u32_f32_sdwa v235, v48 dst_sel:BYTE_2 dst_unused:UNUSED_PRESERVE src0_sel:DWORD
	v_cvt_u32_f32_sdwa v234, v57 dst_sel:BYTE_3 dst_unused:UNUSED_PRESERVE src0_sel:DWORD
	v_cvt_u32_f32_sdwa v235, v49 dst_sel:BYTE_3 dst_unused:UNUSED_PRESERVE src0_sel:DWORD
	s_nop 1
	global_store_dwordx2 v[240:241], v[234:235], off nt
	v_pk_mul_f32 v[34:35], v[34:35], v[146:147] op_sel_hi:[1,0]
	v_pk_mul_f32 v[36:37], v[36:37], v[146:147] op_sel_hi:[1,0]
	v_pk_mul_f32 v[26:27], v[26:27], v[146:147] op_sel_hi:[1,0]
	v_pk_mul_f32 v[28:29], v[28:29], v[146:147] op_sel_hi:[1,0]
	v_exp_f32_e32 v34, v34
	v_exp_f32_e32 v35, v35
	v_exp_f32_e32 v36, v36
	v_exp_f32_e32 v37, v37
	v_exp_f32_e32 v26, v26
	v_exp_f32_e32 v27, v27
	v_exp_f32_e32 v28, v28
	v_exp_f32_e32 v29, v29
	v_pk_add_f32 v[34:35], v[34:35], 1.0 op_sel_hi:[1,0]
	v_pk_add_f32 v[36:37], v[36:37], 1.0 op_sel_hi:[1,0]
	v_pk_add_f32 v[26:27], v[26:27], 1.0 op_sel_hi:[1,0]
	v_pk_add_f32 v[28:29], v[28:29], 1.0 op_sel_hi:[1,0]
	v_rcp_f32_e32 v34, v34
; __device__ __forceinline__ unsigned cvt_pk_bf16(float lo, float hi) { const bf16x2_t r = __builtin_convertvector((f32x2){lo, hi}, bf16x2_t); return __builtin_bit_cast(unsigned, r); }
; __device__ __forceinline__ float bf_lo(unsigned u) { return __uint_as_float(u << 16); }
; __device__ __forceinline__ float bf_hi(unsigned u) { return __uint_as_float(u & 0xffff0000u); }
; __device__ __forceinline__ float sigmoid_f(float x) { return __builtin_amdgcn_rcpf(1.0f + __builtin_amdgcn_exp2f(-1.4426950409f * x)); }
; __device__ __forceinline__ float silu_f(float x) { return x * sigmoid_f(x); }
; __device__ __forceinline__ u32x4 pack8(f32x4 a, f32x4 b) { u32x4 w; w.x = cvt_pk_bf16(a[0], a[1]); w.y = cvt_pk_bf16(a[2], a[3]); w.z = cvt_pk_bf16(b[0], b[1]); w.w = cvt_pk_bf16(b[2], b[3]); return w; }
; __device__ __forceinline__ void unpack8(u32x4 g, f32x4& a, f32x4& b) { a = (f32x4){bf_lo(g.x), bf_hi(g.x), bf_lo(g.y), bf_hi(g.y)}; b = (f32x4){bf_lo(g.z), bf_hi(g.z), bf_lo(g.w), bf_hi(g.w)}; }
;     __device__ __forceinline__ void body_gate(f32x4 (&acc)[2][2][4][2], const Unit& u, int wr, int wc, int fr, int fq, int gbase, const float (&rsv)[2][4]) const {
;     ...
;             const float rs = rsv[ai][m];
; #pragma unroll
;             for (int bj = 0; bj < 2; ++bj) { if (u.half != 0 && bj == 1) continue;
;                 const int gcol = gbase + (bj + (u.half == 2 ? 1 : 0)) * 128 + wc * 32 + 8 * fq;
;                 f32x4 v0 = acc[ai][bj][m][0] * rs, v1 = acc[ai][bj][m][1] * rs;
; #pragma unroll
;                 for (int j = 0; j < 4; ++j) { v0[j] = sigmoid_f(v0[j]); v1[j] = sigmoid_f(v1[j]); }
;                 u32x2 w; w.x = pk_unorm8(v0); w.y = pk_unorm8(v1);
;                 *(u32x2*)((unsigned char*)P + (size_t)row * ROWB + GATE_B0 + gcol) = w;
	v_rcp_f32_e32 v35, v35
	v_rcp_f32_e32 v36, v36
	v_rcp_f32_e32 v37, v37
	v_rcp_f32_e32 v26, v26
	v_rcp_f32_e32 v27, v27
	v_rcp_f32_e32 v28, v28
	v_rcp_f32_e32 v29, v29
	v_pk_fma_f32 v[34:35], v[34:35], s[8:9], 0.5 op_sel_hi:[1,0,0]
	v_pk_fma_f32 v[36:37], v[36:37], s[8:9], 0.5 op_sel_hi:[1,0,0]
	v_pk_fma_f32 v[26:27], v[26:27], s[8:9], 0.5 op_sel_hi:[1,0,0]
	v_pk_fma_f32 v[28:29], v[28:29], s[8:9], 0.5 op_sel_hi:[1,0,0]
	v_cvt_u32_f32_e32 v236, v34
	v_cvt_u32_f32_e32 v237, v26
	v_cvt_u32_f32_sdwa v236, v35 dst_sel:BYTE_1 dst_unused:UNUSED_PRESERVE src0_sel:DWORD
	v_cvt_u32_f32_sdwa v237, v27 dst_sel:BYTE_1 dst_unused:UNUSED_PRESERVE src0_sel:DWORD
	v_cvt_u32_f32_sdwa v236, v36 dst_sel:BYTE_2 dst_unused:UNUSED_PRESERVE src0_sel:DWORD
	v_cvt_u32_f32_sdwa v237, v28 dst_sel:BYTE_2 dst_unused:UNUSED_PRESERVE src0_sel:DWORD
	v_cvt_u32_f32_sdwa v236, v37 dst_sel:BYTE_3 dst_unused:UNUSED_PRESERVE src0_sel:DWORD
	v_cvt_u32_f32_sdwa v237, v29 dst_sel:BYTE_3 dst_unused:UNUSED_PRESERVE src0_sel:DWORD
	s_nop 1
	global_store_dwordx2 v[240:241], v[236:237], off offset:1024 nt
	v_mad_i64_i32 v[238:239], s[4:5], v151, s33, v[232:233]
	v_pk_mul_f32 v[38:39], v[38:39], v[144:145] op_sel_hi:[1,0]
	v_pk_mul_f32 v[40:41], v[40:41], v[144:145] op_sel_hi:[1,0]
	v_pk_mul_f32 v[30:31], v[30:31], v[144:145] op_sel_hi:[1,0]
	v_pk_mul_f32 v[32:33], v[32:33], v[144:145] op_sel_hi:[1,0]
	v_exp_f32_e32 v38, v38
	v_exp_f32_e32 v39, v39
	v_exp_f32_e32 v40, v40
	v_exp_f32_e32 v41, v41
	v_exp_f32_e32 v30, v30
	v_exp_f32_e32 v31, v31
	v_exp_f32_e32 v32, v32
	v_exp_f32_e32 v33, v33
	v_pk_add_f32 v[38:39], v[38:39], 1.0 op_sel_hi:[1,0]
	v_pk_add_f32 v[40:41], v[40:41], 1.0 op_sel_hi:[1,0]
	v_pk_add_f32 v[30:31], v[30:31], 1.0 op_sel_hi:[1,0]
	v_pk_add_f32 v[32:33], v[32:33], 1.0 op_sel_hi:[1,0]
	v_rcp_f32_e32 v38, v38
	v_rcp_f32_e32 v39, v39
	v_rcp_f32_e32 v40, v40
	v_rcp_f32_e32 v41, v41
	v_rcp_f32_e32 v30, v30
	v_rcp_f32_e32 v31, v31
	v_rcp_f32_e32 v32, v32
	v_rcp_f32_e32 v33, v33
	v_pk_fma_f32 v[38:39], v[38:39], s[8:9], 0.5 op_sel_hi:[1,0,0]
	v_pk_fma_f32 v[40:41], v[40:41], s[8:9], 0.5 op_sel_hi:[1,0,0]
	v_pk_fma_f32 v[30:31], v[30:31], s[8:9], 0.5 op_sel_hi:[1,0,0]
	v_pk_fma_f32 v[32:33], v[32:33], s[8:9], 0.5 op_sel_hi:[1,0,0]
	v_cvt_u32_f32_e32 v234, v38
	v_cvt_u32_f32_e32 v235, v30
	v_cvt_u32_f32_sdwa v234, v39 dst_sel:BYTE_1 dst_unused:UNUSED_PRESERVE src0_sel:DWORD
	v_cvt_u32_f32_sdwa v235, v31 dst_sel:BYTE_1 dst_unused:UNUSED_PRESERVE src0_sel:DWORD
	v_cvt_u32_f32_sdwa v234, v40 dst_sel:BYTE_2 dst_unused:UNUSED_PRESERVE src0_sel:DWORD
	v_cvt_u32_f32_sdwa v235, v32 dst_sel:BYTE_2 dst_unused:UNUSED_PRESERVE src0_sel:DWORD
	v_cvt_u32_f32_sdwa v234, v41 dst_sel:BYTE_3 dst_unused:UNUSED_PRESERVE src0_sel:DWORD
	v_cvt_u32_f32_sdwa v235, v33 dst_sel:BYTE_3 dst_unused:UNUSED_PRESERVE src0_sel:DWORD
	s_nop 1
	global_store_dwordx2 v[238:239], v[234:235], off nt
	v_pk_mul_f32 v[18:19], v[18:19], v[144:145] op_sel_hi:[1,0]
	v_pk_mul_f32 v[20:21], v[20:21], v[144:145] op_sel_hi:[1,0]
	v_pk_mul_f32 v[10:11], v[10:11], v[144:145] op_sel_hi:[1,0]
	v_pk_mul_f32 v[12:13], v[12:13], v[144:145] op_sel_hi:[1,0]
	v_exp_f32_e32 v18, v18
	v_exp_f32_e32 v19, v19
	v_exp_f32_e32 v20, v20
	v_exp_f32_e32 v21, v21
	v_exp_f32_e32 v10, v10
	v_exp_f32_e32 v11, v11
	v_exp_f32_e32 v12, v12
	v_exp_f32_e32 v13, v13
	v_pk_add_f32 v[18:19], v[18:19], 1.0 op_sel_hi:[1,0]
	v_pk_add_f32 v[20:21], v[20:21], 1.0 op_sel_hi:[1,0]
	v_pk_add_f32 v[10:11], v[10:11], 1.0 op_sel_hi:[1,0]
	v_pk_add_f32 v[12:13], v[12:13], 1.0 op_sel_hi:[1,0]
	v_rcp_f32_e32 v18, v18
	v_rcp_f32_e32 v19, v19
	v_rcp_f32_e32 v20, v20
	v_rcp_f32_e32 v21, v21
	v_rcp_f32_e32 v10, v10
	v_rcp_f32_e32 v11, v11
	v_rcp_f32_e32 v12, v12
	v_rcp_f32_e32 v13, v13
	v_pk_fma_f32 v[18:19], v[18:19], s[8:9], 0.5 op_sel_hi:[1,0,0]
	v_pk_fma_f32 v[20:21], v[20:21], s[8:9], 0.5 op_sel_hi:[1,0,0]
	v_pk_fma_f32 v[10:11], v[10:11], s[8:9], 0.5 op_sel_hi:[1,0,0]
	v_pk_fma_f32 v[12:13], v[12:13], s[8:9], 0.5 op_sel_hi:[1,0,0]
	v_cvt_u32_f32_e32 v236, v18
	v_cvt_u32_f32_e32 v237, v10
; __device__ __forceinline__ unsigned cvt_pk_bf16(float lo, float hi) { const bf16x2_t r = __builtin_convertvector((f32x2){lo, hi}, bf16x2_t); return __builtin_bit_cast(unsigned, r); }
; __device__ __forceinline__ float bf_lo(unsigned u) { return __uint_as_float(u << 16); }
; __device__ __forceinline__ float bf_hi(unsigned u) { return __uint_as_float(u & 0xffff0000u); }
; __device__ __forceinline__ float sigmoid_f(float x) { return __builtin_amdgcn_rcpf(1.0f + __builtin_amdgcn_exp2f(-1.4426950409f * x)); }
; __device__ __forceinline__ float silu_f(float x) { return x * sigmoid_f(x); }
; __device__ __forceinline__ u32x4 pack8(f32x4 a, f32x4 b) { u32x4 w; w.x = cvt_pk_bf16(a[0], a[1]); w.y = cvt_pk_bf16(a[2], a[3]); w.z = cvt_pk_bf16(b[0], b[1]); w.w = cvt_pk_bf16(b[2], b[3]); return w; }
; __device__ __forceinline__ void unpack8(u32x4 g, f32x4& a, f32x4& b) { a = (f32x4){bf_lo(g.x), bf_hi(g.x), bf_lo(g.y), bf_hi(g.y)}; b = (f32x4){bf_lo(g.z), bf_hi(g.z), bf_lo(g.w), bf_hi(g.w)}; }
;     __device__ __forceinline__ void body_gate(f32x4 (&acc)[2][2][4][2], const Unit& u, int wr, int wc, int fr, int fq, int gbase, const float (&rsv)[2][4]) const {
;     ...
;             const float rs = rsv[ai][m];
; #pragma unroll
;             for (int bj = 0; bj < 2; ++bj) { if (u.half != 0 && bj == 1) continue;
;                 const int gcol = gbase + (bj + (u.half == 2 ? 1 : 0)) * 128 + wc * 32 + 8 * fq;
;                 f32x4 v0 = acc[ai][bj][m][0] * rs, v1 = acc[ai][bj][m][1] * rs;
; #pragma unroll
;                 for (int j = 0; j < 4; ++j) { v0[j] = sigmoid_f(v0[j]); v1[j] = sigmoid_f(v1[j]); }
;                 u32x2 w; w.x = pk_unorm8(v0); w.y = pk_unorm8(v1);
;                 *(u32x2*)((unsigned char*)P + (size_t)row * ROWB + GATE_B0 + gcol) = w;
	v_cvt_u32_f32_sdwa v236, v19 dst_sel:BYTE_1 dst_unused:UNUSED_PRESERVE src0_sel:DWORD
	v_cvt_u32_f32_sdwa v237, v11 dst_sel:BYTE_1 dst_unused:UNUSED_PRESERVE src0_sel:DWORD
	v_cvt_u32_f32_sdwa v236, v20 dst_sel:BYTE_2 dst_unused:UNUSED_PRESERVE src0_sel:DWORD
	v_cvt_u32_f32_sdwa v237, v12 dst_sel:BYTE_2 dst_unused:UNUSED_PRESERVE src0_sel:DWORD
	v_cvt_u32_f32_sdwa v236, v21 dst_sel:BYTE_3 dst_unused:UNUSED_PRESERVE src0_sel:DWORD
	v_cvt_u32_f32_sdwa v237, v13 dst_sel:BYTE_3 dst_unused:UNUSED_PRESERVE src0_sel:DWORD
	s_nop 1
	global_store_dwordx2 v[238:239], v[236:237], off offset:1024 nt
	v_mad_i64_i32 v[240:241], s[4:5], v149, s33, v[232:233]
	v_pk_mul_f32 v[22:23], v[22:23], v[142:143] op_sel_hi:[1,0]
	v_pk_mul_f32 v[24:25], v[24:25], v[142:143] op_sel_hi:[1,0]
	v_pk_mul_f32 v[14:15], v[14:15], v[142:143] op_sel_hi:[1,0]
	v_pk_mul_f32 v[16:17], v[16:17], v[142:143] op_sel_hi:[1,0]
	v_exp_f32_e32 v22, v22
	v_exp_f32_e32 v23, v23
	v_exp_f32_e32 v24, v24
	v_exp_f32_e32 v25, v25
	v_exp_f32_e32 v14, v14
	v_exp_f32_e32 v15, v15
	v_exp_f32_e32 v16, v16
	v_exp_f32_e32 v17, v17
	v_pk_add_f32 v[22:23], v[22:23], 1.0 op_sel_hi:[1,0]
	v_pk_add_f32 v[24:25], v[24:25], 1.0 op_sel_hi:[1,0]
	v_pk_add_f32 v[14:15], v[14:15], 1.0 op_sel_hi:[1,0]
	v_pk_add_f32 v[16:17], v[16:17], 1.0 op_sel_hi:[1,0]
	v_rcp_f32_e32 v22, v22
	v_rcp_f32_e32 v23, v23
	v_rcp_f32_e32 v24, v24
	v_rcp_f32_e32 v25, v25
	v_rcp_f32_e32 v14, v14
	v_rcp_f32_e32 v15, v15
	v_rcp_f32_e32 v16, v16
	v_rcp_f32_e32 v17, v17
	v_pk_fma_f32 v[22:23], v[22:23], s[8:9], 0.5 op_sel_hi:[1,0,0]
	v_pk_fma_f32 v[24:25], v[24:25], s[8:9], 0.5 op_sel_hi:[1,0,0]
	v_pk_fma_f32 v[14:15], v[14:15], s[8:9], 0.5 op_sel_hi:[1,0,0]
	v_pk_fma_f32 v[16:17], v[16:17], s[8:9], 0.5 op_sel_hi:[1,0,0]
	v_cvt_u32_f32_e32 v234, v22
	v_cvt_u32_f32_e32 v235, v14
	v_cvt_u32_f32_sdwa v234, v23 dst_sel:BYTE_1 dst_unused:UNUSED_PRESERVE src0_sel:DWORD
	v_cvt_u32_f32_sdwa v235, v15 dst_sel:BYTE_1 dst_unused:UNUSED_PRESERVE src0_sel:DWORD
	v_cvt_u32_f32_sdwa v234, v24 dst_sel:BYTE_2 dst_unused:UNUSED_PRESERVE src0_sel:DWORD
	v_cvt_u32_f32_sdwa v235, v16 dst_sel:BYTE_2 dst_unused:UNUSED_PRESERVE src0_sel:DWORD
	v_cvt_u32_f32_sdwa v234, v25 dst_sel:BYTE_3 dst_unused:UNUSED_PRESERVE src0_sel:DWORD
	v_cvt_u32_f32_sdwa v235, v17 dst_sel:BYTE_3 dst_unused:UNUSED_PRESERVE src0_sel:DWORD
	s_nop 1
	global_store_dwordx2 v[240:241], v[234:235], off nt
	v_pk_mul_f32 v[6:7], v[6:7], v[142:143] op_sel_hi:[1,0]
	v_pk_mul_f32 v[8:9], v[8:9], v[142:143] op_sel_hi:[1,0]
	v_pk_mul_f32 v[2:3], v[2:3], v[142:143] op_sel_hi:[1,0]
	v_pk_mul_f32 v[4:5], v[4:5], v[142:143] op_sel_hi:[1,0]
	v_exp_f32_e32 v6, v6
	v_exp_f32_e32 v7, v7
	v_exp_f32_e32 v8, v8
	v_exp_f32_e32 v9, v9
	v_exp_f32_e32 v2, v2
	v_exp_f32_e32 v3, v3
	v_exp_f32_e32 v4, v4
	v_exp_f32_e32 v5, v5
	v_pk_add_f32 v[6:7], v[6:7], 1.0 op_sel_hi:[1,0]
	v_pk_add_f32 v[8:9], v[8:9], 1.0 op_sel_hi:[1,0]
	v_pk_add_f32 v[2:3], v[2:3], 1.0 op_sel_hi:[1,0]
	v_pk_add_f32 v[4:5], v[4:5], 1.0 op_sel_hi:[1,0]
	v_rcp_f32_e32 v6, v6
	v_rcp_f32_e32 v7, v7
	v_rcp_f32_e32 v8, v8
	v_rcp_f32_e32 v9, v9
	v_rcp_f32_e32 v2, v2
	v_rcp_f32_e32 v3, v3
	v_rcp_f32_e32 v4, v4
	v_rcp_f32_e32 v5, v5
	v_pk_fma_f32 v[6:7], v[6:7], s[8:9], 0.5 op_sel_hi:[1,0,0]
	v_pk_fma_f32 v[8:9], v[8:9], s[8:9], 0.5 op_sel_hi:[1,0,0]
	v_pk_fma_f32 v[2:3], v[2:3], s[8:9], 0.5 op_sel_hi:[1,0,0]
	v_pk_fma_f32 v[4:5], v[4:5], s[8:9], 0.5 op_sel_hi:[1,0,0]
	v_cvt_u32_f32_e32 v236, v6
	v_cvt_u32_f32_e32 v237, v2
	v_cvt_u32_f32_sdwa v236, v7 dst_sel:BYTE_1 dst_unused:UNUSED_PRESERVE src0_sel:DWORD
	v_cvt_u32_f32_sdwa v237, v3 dst_sel:BYTE_1 dst_unused:UNUSED_PRESERVE src0_sel:DWORD
	v_cvt_u32_f32_sdwa v236, v8 dst_sel:BYTE_2 dst_unused:UNUSED_PRESERVE src0_sel:DWORD
	v_cvt_u32_f32_sdwa v237, v4 dst_sel:BYTE_2 dst_unused:UNUSED_PRESERVE src0_sel:DWORD
	v_cvt_u32_f32_sdwa v236, v9 dst_sel:BYTE_3 dst_unused:UNUSED_PRESERVE src0_sel:DWORD
	v_cvt_u32_f32_sdwa v237, v5 dst_sel:BYTE_3 dst_unused:UNUSED_PRESERVE src0_sel:DWORD
	s_nop 1
	global_store_dwordx2 v[240:241], v[236:237], off offset:1024 nt
	s_mov_b64 s[4:5], 0
